# residual-stream init of the slab-1 rows moved from phase 0 to the idle CUs of phase 1's last round (second pass over kind 0, 236 CUs); phase 0 initialises slab-0 rows only
# baseline (speedup 1.0000x reference)
; __device__ __forceinline__ void p0_prologue(ArgP ap, unsigned char* lds, int tid) {
;     const int lane = tid & 63, wave = tid >> 6;
;     float* scr = (float*)(lds + wave * 16384);
;     int gdim = gridDim.x; asm volatile("" : "+s"(gdim));
;     const int gw = blockIdx.x * 8 + wave, NGW = gdim * 8;
;     unsigned char* dob = (unsigned char*)ap->out;
;     bf16* WHG = (bf16*)(dob + DO_WHG); bf16* WHGO = (bf16*)(dob + DO_WHGO); bf16* WF0I = (bf16*)(dob + DO_WF0I); bf16* WF0O = (bf16*)(dob + DO_WF0O);
;     bf16* WRW1 = (bf16*)(dob + DO_WRW1); bf16* WLORA = (bf16*)(dob + DO_WLORA); bf16* WRWO = (bf16*)(dob + DO_WRWO); bf16* WG2 = (bf16*)(dob + DO_WG2); bf16* WF1I = (bf16*)(dob + DO_WF1I); bf16* WF1O = (bf16*)(dob + DO_WF1O);
;     const float* mu = ap->in[10];
;     constexpr int I_HG = 16 * 160, I_SQ = 16 * 32, I_FI = 16 * 176, I_FO = 44 * 32, I_L64 = 16 * 2, I_G1 = 16 * 5, I_G2 = 4 * 32;
;     constexpr int NITEMS = I_HG + I_SQ + 2 * I_FI + 2 * I_FO + 3 * I_SQ + 4 * I_L64 + 4 * I_L64 + 2 * I_G1 + I_SQ + I_G2;
;     for (int it = gw; it < NITEMS; it += NGW) {
;         int r = it;
;         if (r < I_HG) { const int kb = r / 160, nb = r % 160; tr_item(ap->in[6], 5120, 1024, 64 * kb, 32 * nb, WHG, 1024, 32 * nb, 0, ap->in[3], scr, lane, nullptr, false); continue; } r -= I_HG;
.LBB0_753:
	s_andn2_b64 vcc, exec, s[0:1]
	s_cbranch_vccnz .LBB0_961
	s_mov_b32 s1, s94
	v_ashrrev_i32_e32 v13, 6, v202
	s_lshl_b32 s0, s1, 3
	s_waitcnt lgkmcnt(0)
	v_add_u32_e32 v18, s93, v13
	s_add_u32 s8, s4, 0x6380000
	s_movk_i32 s2, 0x3720
	v_and_b32_e32 v11, 63, v203
	s_addc_u32 s9, s5, 0
	s_cmp_eq_u32 s99, 1
	s_cselect_b32 s2, 0, s2
	v_cmp_gt_i32_e32 vcc, s2, v18
	s_and_saveexec_b64 s[10:11], vcc
	s_cbranch_execz .LBB0_928
	v_readlane_b32 s12, v255, 5
	v_readlane_b32 s13, v255, 6
	s_load_dwordx2 s[12:13], s[12:13], 0x50
	v_and_b32_e32 v6, 7, v203
	v_lshlrev_b32_e32 v4, 14, v13
	s_waitcnt vmcnt(0)
	v_lshrrev_b32_e32 v29, 3, v11
	v_lshlrev_b32_e32 v0, 4, v6
	v_add_u32_e32 v5, 0, v4
	v_mul_u32_u24_e32 v7, 0x420, v6
	v_lshl_add_u64 v[2:3], s[4:5], 0, v[0:1]
	v_lshlrev_b32_e32 v0, 2, v29
	s_mov_b64 s[20:21], 0x5d80000
	v_readlane_b32 s2, v254, 16
	s_mov_b64 s[16:17], 0x6e80000
	v_add3_u32 v52, v5, v7, v0
	v_lshlrev_b32_e32 v0, 5, v6
	v_lshl_add_u64 v[20:21], v[2:3], 0, s[20:21]
	s_mov_b64 s[20:21], 0x4b00000
	v_lshl_add_u32 v58, v13, 1, s2
	v_readlane_b32 s2, v254, 17
	v_lshrrev_b32_e32 v19, 5, v11
	v_lshl_add_u64 v[14:15], v[2:3], 0, s[16:17]
	s_mov_b64 s[16:17], 0x6c80000
	s_waitcnt lgkmcnt(0)
	s_cmp_lg_u64 s[12:13], 0
	v_lshl_add_u64 v[22:23], v[2:3], 0, s[20:21]
	s_mov_b64 s[20:21], 0x4100000
	v_lshl_add_u32 v59, v13, 5, s2
	v_readlane_b32 s2, v254, 18
	v_lshl_add_u64 v[30:31], s[12:13], 0, v[0:1]
	s_mov_b64 s[12:13], 0x5000
	v_and_b32_e32 v10, 31, v203
	v_lshl_add_u64 v[16:17], v[2:3], 0, s[16:17]
	v_lshl_add_u64 v[24:25], v[2:3], 0, s[20:21]
	v_mul_u32_u24_e32 v2, 0x84, v19
	v_add_u32_e32 v82, s2, v13
	v_readlane_b32 s2, v254, 19
	v_lshl_add_u64 v[32:33], v[30:31], 0, s[12:13]
	s_mov_b64 s[12:13], 0x4000
	v_or_b32_e32 v2, v4, v2
	v_lshlrev_b32_e32 v26, 2, v10
	v_add_u32_e32 v83, s2, v13
	v_readlane_b32 s2, v254, 20
	v_lshl_add_u64 v[34:35], v[30:31], 0, s[12:13]
	s_mov_b64 s[12:13], 0x1000
	v_lshlrev_b32_e32 v12, 3, v6
	v_or_b32_e32 v53, 8, v29
	v_or_b32_e32 v54, 16, v29
	v_or_b32_e32 v55, 24, v29
	s_mov_b64 s[16:17], 0
	s_cselect_b64 s[18:19], -1, 0
	v_add3_u32 v56, v2, v26, 0
	v_mov_b32_e32 v27, v1
	v_or_b32_e32 v57, 0xffff92ce, v19
	s_lshl_b32 s24, s1, 4
	s_lshl_b32 s54, s1, 8
	v_or_b32_e32 v60, 0xffff92cc, v19
	v_or_b32_e32 v61, 0xffff92ca, v19
	v_or_b32_e32 v62, 0xffff92c8, v19
	v_or_b32_e32 v63, 0xffff92c6, v19
	v_or_b32_e32 v64, 0xffff92c4, v19
	v_or_b32_e32 v65, 0xffff92c2, v19
	v_or_b32_e32 v66, 0xffff92c0, v19
	v_or_b32_e32 v67, 0xffff96ce, v19
	v_or_b32_e32 v68, 0xffff96cc, v19
	v_or_b32_e32 v69, 0xffff96ca, v19
	v_or_b32_e32 v70, 0xffff96c8, v19
	v_or_b32_e32 v71, 0xffff96c6, v19
	v_or_b32_e32 v72, 0xffff96c4, v19
	v_or_b32_e32 v73, 0xffff96c2, v19
	v_or_b32_e32 v74, 0xffff96c0, v19
	v_or_b32_e32 v75, 14, v19
	v_or_b32_e32 v76, 12, v19
	v_or_b32_e32 v77, 10, v19
	v_or_b32_e32 v78, 8, v19
	v_or_b32_e32 v79, 6, v19
	v_or_b32_e32 v80, 4, v19
	v_or_b32_e32 v81, 2, v19
	v_add_lshl_u32 v84, s2, v13, 1
	v_or_b32_e32 v85, 0xffffec0e, v19
	v_or_b32_e32 v86, 0xffffec0c, v19
	v_or_b32_e32 v87, 0xffffec0a, v19
	v_or_b32_e32 v88, 0xffffec08, v19
	v_or_b32_e32 v89, 0xffffec06, v19
	v_or_b32_e32 v90, 0xffffec04, v19
	v_or_b32_e32 v91, 0xffffec02, v19
	v_or_b32_e32 v92, 0xffffec00, v19
	v_bfe_u32 v28, v203, 5, 1
	v_mov_b32_e32 v93, v18
	v_lshl_add_u64 v[36:37], v[30:31], 0, s[12:13]
	s_branch .LBB0_759

; __device__ __forceinline__ void p0_prologue(ArgP ap, unsigned char* lds, int tid) {
;     ...
;     {
;         const int gt = blockIdx.x * 512 + tid, NGT = gdim * 512;
;         for (int i = gt; i < 96 * 256; i += NGT) { const int rr = i >> 8, cc = i & 255;
;             unsigned zz = 0u; asm volatile("" : "+v"(zz)); *(u32x4_t*)(WLORA + (size_t)(416 + rr) * 2048 + cc * 8) = (u32x4_t){zz, zz, zz, zz}; }
;     }
.LBB0_928:
	s_or_b64 exec, exec, s[10:11]
	s_cmp_eq_u32 s99, 1
	s_cbranch_scc1 .LBB0_931
	v_add_u32_e32 v2, s95, v202
	v_cmp_gt_i32_e32 vcc, s64, v2
	s_and_saveexec_b64 s[10:11], vcc
	s_cbranch_execz .LBB0_931
	s_lshl_b32 s2, s1, 9
	v_lshlrev_b32_e32 v3, 3, v2
	s_lshl_b32 s1, s1, 12
	s_mov_b64 s[12:13], 0

; __device__ __forceinline__ unsigned pk2(float lo, float hi) { const f32x2_cv v = {lo, hi}; const bf16x2_cv b = __builtin_convertvector(v, bf16x2_cv); return __builtin_bit_cast(unsigned, b); }
; __device__ __forceinline__ void p0_prologue(ArgP ap, unsigned char* lds, int tid) {
;     ...
;     bf16* HB = (bf16*)(dob + DO_HB); float* ssq0 = (float*)(ap->ws + WS_SSQ);
;     for (int r = gw; r < TROWS; r += NGW) {
;         int o, tokbase; bool pad = false;
;         if (r < 8256) { o = r; tokbase = 16384; } else if (r < 16512) { o = r - 8256; tokbase = 24576; } else if (r < 16640) { pad = true; o = 0; tokbase = 0; }
;         else if (r < 33088) { o = r - 16640; tokbase = 0; } else { pad = true; o = 0; tokbase = 0; }
;         if (o < 48) pad = true;
;         const float* src = nullptr;
;         if (!pad) { if (o < 64) src = ap->in[2] + (size_t)(o - 48) * 1024; else { const int g = tokbase + o - 64; src = (g < 16384) ? ap->in[0] + (size_t)g * 1024 : ap->in[1] + (size_t)(g - 16384) * 1024; } }
;         float s = 0.f;
; #pragma unroll
;         for (int j = 0; j < 4; ++j) { f32x4_t v = (f32x4_t){0.f, 0.f, 0.f, 0.f}; if (src) v = __builtin_nontemporal_load((const f32x4_t*)(src + 4 * lane + 256 * j));
;             s += v[0] * v[0] + v[1] * v[1] + v[2] * v[2] + v[3] * v[3];
;             u32x2_t w; w.x = pk2(v[0], v[1]); w.y = pk2(v[2], v[3]); *(u32x2_t*)(HB + (size_t)r * 1024 + 4 * lane + 256 * j) = w; }
;         s = wave_sum(s); if (lane == 0) ssq0[r] = s;
;     }
.LBB0_931:
	s_or_b64 exec, exec, s[10:11]
	v_readlane_b32 s54, v254, 58
	s_mov_b32 s1, 0x8200
	v_readlane_b32 s55, v254, 59
	s_mov_b32 s101, 0x81ff
	s_cmp_lg_u32 s94, 0x100
	s_cbranch_scc1 .Linit_par_done
	s_cmp_eq_u32 s99, 1
	s_cbranch_scc1 .Linit_host
	s_movk_i32 s1, 0x4100
	s_movk_i32 s101, 0x40ff
	s_branch .Linit_par_done
.Linit_host:
	v_add_u32_e32 v18, 0x4060, v18
	s_movk_i32 s0, 0x760
.Linit_par_done:
	v_cmp_gt_i32_e32 vcc, s1, v18
	s_and_saveexec_b64 s[8:9], vcc
	s_cbranch_execz .LBB0_960
	v_and_b32_e32 v2, 64, v198
	v_add_u32_e32 v2, 64, v2
	v_xor_b32_e32 v3, 1, v198
	v_cmp_lt_i32_e32 vcc, v3, v2
	v_ashrrev_i32_e32 v19, 31, v18
	v_readlane_b32 s1, v254, 21
	v_cndmask_b32_e32 v3, v198, v3, vcc
	s_waitcnt vmcnt(0)
	v_lshlrev_b32_e32 v26, 2, v3
	v_xor_b32_e32 v3, 2, v198
	v_cmp_lt_i32_e32 vcc, v3, v2
	v_lshlrev_b32_e32 v0, 2, v11
	v_add_u32_e32 v32, s1, v13
	s_cmp_eq_u32 s99, 1
	s_cselect_b32 s100, 0x4060, 0
	v_add_u32_e32 v32, s100, v32
	v_cndmask_b32_e32 v3, v198, v3, vcc
	v_lshlrev_b32_e32 v27, 2, v3
	v_xor_b32_e32 v3, 4, v198
	v_cmp_lt_i32_e32 vcc, v3, v2
	s_ashr_i32 s1, s0, 31
	v_cmp_eq_u32_e64 s[36:37], 0, v11
	v_cndmask_b32_e32 v3, v198, v3, vcc
	v_lshlrev_b32_e32 v28, 2, v3
	v_xor_b32_e32 v3, 8, v198
	v_cmp_lt_i32_e32 vcc, v3, v2
	v_lshl_add_u64 v[20:21], v[18:19], 2, s[6:7]
	s_lshl_b64 s[6:7], s[0:1], 2
	v_cndmask_b32_e32 v3, v198, v3, vcc
	v_lshlrev_b32_e32 v29, 2, v3
	v_xor_b32_e32 v3, 16, v198
	v_cmp_lt_i32_e32 vcc, v3, v2
	s_mov_b64 s[10:11], 0
	v_lshlrev_b32_e32 v0, 2, v0
	v_cndmask_b32_e32 v3, v198, v3, vcc
	v_lshlrev_b32_e32 v30, 2, v3
	v_xor_b32_e32 v3, 32, v198
	v_cmp_lt_i32_e32 vcc, v3, v2
	s_nop 1
	v_cndmask_b32_e32 v2, v198, v3, vcc
	v_lshlrev_b32_e32 v31, 2, v2
	v_lshlrev_b64 v[2:3], 11, v[18:19]
	v_lshl_or_b32 v2, v11, 3, v2
	v_lshl_add_u64 v[2:3], s[4:5], 0, v[2:3]
	s_mov_b64 s[4:5], 0x400
	v_lshl_add_u64 v[22:23], v[2:3], 0, s[4:5]
	s_lshl_b64 s[4:5], s[0:1], 11
	s_branch .LBB0_934
.LBB0_933:
	s_or_b64 exec, exec, s[12:13]
	v_add_u32_e32 v32, s0, v32
	v_add_u32_e32 v2, 0x8140, v32
	s_mov_b32 s1, s101
	v_cmp_lt_i32_e32 vcc, s1, v2
	v_add_u32_e32 v18, s0, v18
	v_lshl_add_u64 v[20:21], v[20:21], 0, s[6:7]
	s_or_b64 s[10:11], vcc, s[10:11]
	v_lshl_add_u64 v[22:23], v[22:23], 0, s[4:5]
	s_andn2_b64 exec, exec, s[10:11]
	s_cbranch_execz .LBB0_960

; __global__ void __launch_bounds__(512, 2) fwd_mega(Args a_) {
;     ...
;         int kind = 15, slab = 0;
;         if (ph == 0) kind = 0;
;         else if (ph <= 10) { const int q = (ph - 1) % 5; slab = (ph - 1) / 5; kind = q == 0 ? 1 : (q == 1 ? 14 : (q == 2 ? 2 : (q == 3 ? 3 : 4))); }
;         else if (ph == 11) kind = 5; else if (ph == 12) kind = 6;
;         else if (ph <= 26) { kind = 7 + (ph - 13) % 7; slab = (ph - 13) / 7; }
;         else if (ph == 27) { kind = 5; slab = 1; } else if (ph == 28) { kind = 6; slab = 1; }
;     ...
;         default: if (PHM & 2048) final_norm((const bf16*)(ws + WS_HBNEW), (const float*)(ws + WS_PB), ap->in[5], ap->out, tid); break;
;         }
;         if (phc < 29) { unsigned z2 = 0u; asm volatile("" : "+v"(z2)); const int t2 = wave_s * 64 + (int)__builtin_amdgcn_mbcnt_hi(~0u, __builtin_amdgcn_mbcnt_lo(~0u, z2)); xcd_barrier(xbar, t2); }
.LBB0_961:
	s_cmp_eq_u32 s99, 1
	s_cbranch_scc1 .Lpre_back
	s_cmp_lg_u32 s94, 0x100
	s_cbranch_scc1 .Lpre_none
	s_cmp_eq_u32 s83, 1
	s_cbranch_scc1 .Lpre_chk0
	s_cmp_eq_u32 s83, 5
	s_cbranch_scc1 .Lpre_chk1
	s_cmp_eq_u32 s83, 10
	s_cselect_b32 s100, 0, 1
	s_cbranch_scc1 .Lpre_chk
	s_cmp_eq_u32 s83, 26
	s_cbranch_scc0 .Lpre_none

; __global__ void __launch_bounds__(512, 2) fwd_mega(Args a_) {
;     ...
;         int kind = 15, slab = 0;
;         if (ph == 0) kind = 0;
;         else if (ph <= 10) { const int q = (ph - 1) % 5; slab = (ph - 1) / 5; kind = q == 0 ? 1 : (q == 1 ? 14 : (q == 2 ? 2 : (q == 3 ? 3 : 4))); }
;         else if (ph == 11) kind = 5; else if (ph == 12) kind = 6;
;         else if (ph <= 26) { kind = 7 + (ph - 13) % 7; slab = (ph - 13) / 7; }
;         else if (ph == 27) { kind = 5; slab = 1; } else if (ph == 28) { kind = 6; slab = 1; }
.Lpre_chk0:
	s_cmp_lt_u32 s96, 20
	s_cbranch_scc1 .Lpre_none
	s_mov_b32 s99, 1
	s_mov_b32 s65, 0
	s_mov_b32 s40, 0
	s_branch .Lpre_go
